# hgrn2: hoist loop-invariant norm-gain loads out of chunk loop (removes 8 serialized vmcnt(0) round trips per chunk)
# speedup vs baseline: 1.0099x; 1.0099x over previous
; DI void hgrn2_block(const Args& a, unsigned char* lds, int bh, int tid, int wave, int lane) {
;     const int b = bh >> 3, h = bh & 7, tok0 = b * SEQ_;
;     const bf16_t* Y1 = (const bf16_t*)(a.ws + WS_R); bf16_t* AB = (bf16_t*)(a.ws + WS_AB);
;     bf16_t* Qt = (bf16_t*)(lds + HG_QT); bf16_t* Kt = (bf16_t*)(lds + HG_KT); bf16_t* Qi = (bf16_t*)(lds + HG_QI); bf16_t* KdT = (bf16_t*)(lds + HG_KDT);
;     bf16_t* VTl = (bf16_t*)(lds + HG_VT); bf16_t* ST = (bf16_t*)(lds + HG_ST); bf16_t* P = (bf16_t*)(lds + HG_P);
;     float* seg = (float*)(lds + HG_SEG); float* dec = (float*)(lds + HG_DEC); float* rss = (float*)(lds + HG_RSS);
;     const int r = lane & 31, hh = lane >> 5;
;     for (int i = tid; i < (HG_P - HG_ST) / 4 + 9216 / 4; i += NTHR) ((unsigned*)(lds + HG_ST))[i] = 0u;
;     const int k = tid & 127, tq = tid >> 7;
;     const int ct = wave >> 1, vt2 = (wave & 1) * 2;
;     f32x16 S0, S1;
; #pragma unroll
;     for (int e = 0; e < 16; ++e) { S0[e] = 0.f; S1[e] = 0.f; }
;     const int vt = wave & 3, tc = wave >> 2;
;     const float* gn = a.in[10];
;     __syncthreads();
;     unsigned short pq[16], pg[16], pv[16]; u32x4 phg[2];
;     { const bf16_t* base = Y1 + (size_t)(tok0 + 16 * tq) * NY1 + h * 128 + k;
; #pragma unroll
;       for (int j = 0; j < 16; ++j) { pq[j] = base[(size_t)j * NY1 + 2048]; pg[j] = base[(size_t)j * NY1 + 3072]; pv[j] = base[(size_t)j * NY1 + 4096]; }
;       const u32x4* hgp = (const u32x4*)(Y1 + (size_t)(tok0 + (tid >> 3)) * NY1 + 5120 + h * 128 + (tid & 7) * 16); phg[0] = hgp[0]; phg[1] = hgp[1]; }
.LBB0_225:
	s_or_b64 exec, exec, s[8:9]
	s_add_u32 s90, s84, 0x18dcc000
	s_addc_u32 s91, s85, 0
	s_ashr_i32 s8, s2, 2
	s_and_b32 s8, s8, -2
	s_add_i32 s10, s8, s3
	s_and_b64 s[8:9], s[6:7], exec
	s_cselect_b32 s9, s2, s10
	s_lshl_b32 s8, s9, 8
	s_and_b32 s8, s8, 0xfffff800
	s_lshl_b32 s9, s9, 7
	v_ashrrev_i32_e32 v32, 7, v4
	s_and_b32 s87, s9, 0x380
	v_lshl_add_u32 v34, v32, 4, s8
	s_movk_i32 s72, 0x3000
	v_mov_b64_e32 v[2:3], s[90:91]
	s_mov_b32 s93, 0
	v_and_b32_e32 v33, 0x7f, v4
	v_mad_i64_i32 v[6:7], s[10:11], v34, s72, v[2:3]
	s_lshl_b32 s92, s87, 1
	v_lshl_add_u64 v[6:7], v[6:7], 0, s[92:93]
	v_lshlrev_b32_e32 v66, 1, v33
	v_mov_b32_e32 v67, 0
	v_lshl_add_u64 v[6:7], v[6:7], 0, v[66:67]
	s_movk_i32 s9, 0x1000
	v_add_co_u32_e32 v8, vcc, s9, v6
	s_movk_i32 s9, 0x2000
	s_nop 0
	v_addc_co_u32_e32 v9, vcc, 0, v7, vcc
	v_add_co_u32_e32 v10, vcc, s9, v6
	s_movk_i32 s10, 0x4000
	s_nop 0
	v_addc_co_u32_e32 v11, vcc, 0, v7, vcc
	v_add_co_u32_e32 v12, vcc, s10, v6
	s_movk_i32 s10, 0x5000
	s_nop 0
	v_addc_co_u32_e32 v13, vcc, 0, v7, vcc
	v_add_co_u32_e32 v14, vcc, s10, v6
	s_movk_i32 s10, 0x7000
	s_nop 0
	v_addc_co_u32_e32 v15, vcc, 0, v7, vcc
	v_add_co_u32_e32 v16, vcc, s10, v6
	s_mov_b32 s10, 0x8000
	s_nop 0
	v_addc_co_u32_e32 v17, vcc, 0, v7, vcc
	v_add_co_u32_e32 v18, vcc, s10, v6
	s_mov_b32 s10, 0xa000
	s_nop 0
	v_addc_co_u32_e32 v19, vcc, 0, v7, vcc
	v_add_co_u32_e32 v20, vcc, s10, v6
	s_mov_b32 s10, 0xb000
	s_nop 0
	v_addc_co_u32_e32 v21, vcc, 0, v7, vcc
	v_add_co_u32_e32 v22, vcc, s10, v6
	s_mov_b32 s10, 0xd000
	s_nop 0
	v_addc_co_u32_e32 v23, vcc, 0, v7, vcc
	s_waitcnt vmcnt(0) lgkmcnt(0)
	s_barrier
	global_load_ushort v43, v[10:11], off offset:-4096
	global_load_ushort v38, v[10:11], off
	global_load_ushort v44, v[14:15], off offset:-4096
	global_load_ushort v39, v[14:15], off
	global_load_ushort v40, v[18:19], off offset:-4096
	global_load_ushort v36, v[18:19], off
	global_load_ushort v41, v[22:23], off offset:-4096
	global_load_ushort v37, v[22:23], off
	v_add_co_u32_e32 v10, vcc, s10, v6
	s_mov_b32 s10, 0xe000
	s_nop 0
	v_addc_co_u32_e32 v11, vcc, 0, v7, vcc
	v_add_co_u32_e32 v14, vcc, s10, v6
	s_mov_b32 s10, 0x10000
	s_nop 0
	v_addc_co_u32_e32 v15, vcc, 0, v7, vcc
	v_add_co_u32_e32 v18, vcc, s10, v6
	s_mov_b32 s10, 0x11000
	s_nop 0
	v_addc_co_u32_e32 v19, vcc, 0, v7, vcc
	v_add_co_u32_e32 v22, vcc, s10, v6
	s_mov_b32 s10, 0x13000
	s_nop 0
	v_addc_co_u32_e32 v23, vcc, 0, v7, vcc
	v_add_co_u32_e32 v24, vcc, s10, v6
	s_mov_b32 s10, 0x14000
	s_nop 0
	v_addc_co_u32_e32 v25, vcc, 0, v7, vcc
	v_add_co_u32_e32 v26, vcc, s10, v6
	s_mov_b32 s10, 0x16000
	s_nop 0
	v_addc_co_u32_e32 v27, vcc, 0, v7, vcc
	v_add_co_u32_e32 v28, vcc, s10, v6
	s_mov_b32 s10, 0x17000
	s_nop 0
	v_addc_co_u32_e32 v29, vcc, 0, v7, vcc
	v_add_co_u32_e32 v30, vcc, s10, v6
	s_mov_b32 s10, 0x19000
	s_nop 0
	v_addc_co_u32_e32 v31, vcc, 0, v7, vcc
	global_load_ushort v73, v[8:9], off offset:2048
	global_load_ushort v74, v[12:13], off offset:2048
	global_load_ushort v75, v[16:17], off offset:2048
	global_load_ushort v76, v[20:21], off offset:2048
	global_load_ushort v77, v[10:11], off offset:2048
	global_load_ushort v79, v[18:19], off offset:2048
	global_load_ushort v82, v[24:25], off offset:2048
	global_load_ushort v89, v[28:29], off offset:2048
	global_load_ushort v157, v[14:15], off offset:-4096
	global_load_ushort v47, v[14:15], off
	global_load_ushort v158, v[22:23], off offset:-4096
	global_load_ushort v48, v[22:23], off
	global_load_ushort v153, v[26:27], off offset:-4096
	global_load_ushort v45, v[26:27], off
	global_load_ushort v155, v[30:31], off offset:-4096
	global_load_ushort v46, v[30:31], off
	v_add_co_u32_e32 v8, vcc, s10, v6
	s_mov_b32 s10, 0x1a000
	s_nop 0
	v_addc_co_u32_e32 v9, vcc, 0, v7, vcc
	v_add_co_u32_e32 v10, vcc, s10, v6
	s_mov_b32 s10, 0x1c000
	s_nop 0
	v_addc_co_u32_e32 v11, vcc, 0, v7, vcc
	v_add_co_u32_e32 v12, vcc, s10, v6
	s_mov_b32 s10, 0x1d000
	s_nop 0
	v_addc_co_u32_e32 v13, vcc, 0, v7, vcc
	v_add_co_u32_e32 v14, vcc, s10, v6
	s_mov_b32 s10, 0x1f000
	s_nop 0
	v_addc_co_u32_e32 v15, vcc, 0, v7, vcc
	v_add_co_u32_e32 v16, vcc, s10, v6
	s_mov_b32 s10, 0x20000
	s_nop 0
	v_addc_co_u32_e32 v17, vcc, 0, v7, vcc
	v_add_co_u32_e32 v18, vcc, s10, v6
	s_mov_b32 s10, 0x22000
	s_nop 0
	v_addc_co_u32_e32 v19, vcc, 0, v7, vcc
	v_add_co_u32_e32 v20, vcc, s10, v6
	s_mov_b32 s10, 0x23000
	s_nop 0
	v_addc_co_u32_e32 v21, vcc, 0, v7, vcc
	v_add_co_u32_e32 v22, vcc, s10, v6
	s_mov_b32 s10, 0x25000
	s_nop 0
	v_addc_co_u32_e32 v23, vcc, 0, v7, vcc
	global_load_ushort v165, v[10:11], off offset:-4096
	global_load_ushort v151, v[10:11], off
	global_load_ushort v166, v[14:15], off offset:-4096
	global_load_ushort v152, v[14:15], off
	global_load_ushort v160, v[18:19], off offset:-4096
	global_load_ushort v49, v[18:19], off
	global_load_ushort v162, v[22:23], off offset:-4096
	global_load_ushort v150, v[22:23], off
	v_add_co_u32_e32 v10, vcc, s10, v6
	s_mov_b32 s10, 0x26000
	s_nop 0
	v_addc_co_u32_e32 v11, vcc, 0, v7, vcc
	v_add_co_u32_e32 v14, vcc, s10, v6
	s_mov_b32 s10, 0x28000
	s_nop 0
	v_addc_co_u32_e32 v15, vcc, 0, v7, vcc
	v_add_co_u32_e32 v18, vcc, s10, v6
	s_mov_b32 s10, 0x29000
	s_nop 0
	v_addc_co_u32_e32 v19, vcc, 0, v7, vcc
	v_add_co_u32_e32 v22, vcc, s10, v6
	s_mov_b32 s10, 0x2b000
	s_nop 0
	v_addc_co_u32_e32 v23, vcc, 0, v7, vcc
	v_add_co_u32_e32 v24, vcc, s10, v6
	s_mov_b32 s10, 0x2c000
	s_nop 0
	v_addc_co_u32_e32 v25, vcc, 0, v7, vcc
	v_add_co_u32_e32 v26, vcc, s10, v6
	s_mov_b32 s10, 0x2e000
	s_nop 0
	v_addc_co_u32_e32 v27, vcc, 0, v7, vcc
	v_add_co_u32_e32 v28, vcc, s10, v6
	s_mov_b32 s10, 0x2f000
	s_nop 0
	v_addc_co_u32_e32 v29, vcc, 0, v7, vcc
; DI void hgrn2_block(const Args& a, unsigned char* lds, int bh, int tid, int wave, int lane) {
;     ...
;     const int r = lane & 31, hh = lane >> 5;
;     for (int i = tid; i < (HG_P - HG_ST) / 4 + 9216 / 4; i += NTHR) ((unsigned*)(lds + HG_ST))[i] = 0u;
;     const int k = tid & 127, tq = tid >> 7;
;     const int ct = wave >> 1, vt2 = (wave & 1) * 2;
;     f32x16 S0, S1;
; #pragma unroll
;     for (int e = 0; e < 16; ++e) { S0[e] = 0.f; S1[e] = 0.f; }
;     const int vt = wave & 3, tc = wave >> 2;
;     const float* gn = a.in[10];
;     __syncthreads();
;     unsigned short pq[16], pg[16], pv[16]; u32x4 phg[2];
;     { const bf16_t* base = Y1 + (size_t)(tok0 + 16 * tq) * NY1 + h * 128 + k;
; #pragma unroll
;       for (int j = 0; j < 16; ++j) { pq[j] = base[(size_t)j * NY1 + 2048]; pg[j] = base[(size_t)j * NY1 + 3072]; pv[j] = base[(size_t)j * NY1 + 4096]; }
;       const u32x4* hgp = (const u32x4*)(Y1 + (size_t)(tok0 + (tid >> 3)) * NY1 + 5120 + h * 128 + (tid & 7) * 16); phg[0] = hgp[0]; phg[1] = hgp[1]; }
	v_add_co_u32_e32 v6, vcc, s10, v6
	s_mov_b64 s[94:95], 0x2800
	s_nop 0
	v_addc_co_u32_e32 v7, vcc, 0, v7, vcc
	global_load_ushort v110, v[8:9], off offset:2048
	global_load_ushort v111, v[12:13], off offset:2048
	global_load_ushort v114, v[16:17], off offset:2048
	global_load_ushort v117, v[20:21], off offset:2048
	global_load_ushort v118, v[10:11], off offset:2048
	global_load_ushort v123, v[18:19], off offset:2048
	global_load_ushort v126, v[24:25], off offset:2048
	global_load_ushort v127, v[28:29], off offset:2048
	global_load_ushort v170, v[14:15], off offset:-4096
	global_load_ushort v161, v[14:15], off
	global_load_ushort v171, v[22:23], off offset:-4096
	global_load_ushort v163, v[22:23], off
	global_load_ushort v167, v[26:27], off offset:-4096
	global_load_ushort v159, v[26:27], off
	global_load_ushort v169, v[6:7], off offset:-4096
	global_load_ushort v164, v[6:7], off
	v_ashrrev_i32_e32 v7, 3, v4
	v_add_u32_e32 v78, s8, v7
	v_lshlrev_b32_e32 v6, 4, v4
	v_mad_i64_i32 v[2:3], s[10:11], v78, s72, v[2:3]
	v_and_b32_e32 v6, 0x70, v6
	v_lshl_add_u64 v[2:3], v[2:3], 0, s[92:93]
	v_lshlrev_b32_e32 v8, 1, v6
	v_mov_b32_e32 v9, v67
	v_lshl_add_u64 v[2:3], v[2:3], 0, v[8:9]
	v_lshl_add_u64 v[10:11], v[2:3], 0, s[94:95]
	v_add_co_u32_e32 v2, vcc, s9, v2
	s_bfe_u32 s18, s81, 0x20006
	s_nop 0
	v_addc_co_u32_e32 v3, vcc, 0, v3, vcc
	global_load_dwordx4 v[54:57], v[2:3], off offset:2048
	global_load_dwordx4 v[50:53], v[10:11], off offset:16
	s_and_b32 s16, s81, 64
	s_ashr_i32 s19, s81, 8
	s_add_i32 s10, 0, 0x20800
	s_add_u32 s8, s90, s92
	s_addc_u32 s9, s91, 0
	s_add_i32 s17, 0, 0x11400
	s_add_i32 s73, 0, 0x21000
	s_cmp_lt_i32 s80, 3
	s_cselect_b64 s[96:97], -1, 0
	s_cmp_eq_u32 s80, 2
	v_lshlrev_b32_e32 v2, 2, v33
	s_cselect_b32 s20, 32, 0
	v_add_u32_e32 v81, s10, v2
	v_mul_u32_u24_e32 v9, 0x48, v33
	v_add_u32_e32 v85, s73, v2
	s_cmp_lt_u32 s81, 64
	v_or_b32_e32 v2, s20, v72
	v_lshlrev_b32_e32 v3, 5, v32
	v_lshlrev_b32_e32 v9, 1, v9
	v_mul_u32_u24_e32 v2, 0x110, v2
	v_lshlrev_b32_e32 v86, 4, v5
	s_cselect_b32 s22, 0, 32
	s_and_b32 s23, s81, 0xffffff80
	v_add3_u32 v83, 0, v3, v9
	v_add3_u32 v84, s17, v3, v9
	v_add3_u32 v87, 0, v2, v86
	v_or_b32_e32 v2, s22, v72
	v_lshl_or_b32 v9, s18, 5, v72
	s_add_i32 s73, s73, s23
	s_ashr_i32 s23, s81, 2
	s_movk_i32 s14, 0x80
	v_mul_u32_u24_e32 v3, 0x110, v2
	v_lshlrev_b32_e32 v156, 2, v5
	v_mul_u32_u24_e32 v10, 0x110, v9
	s_add_i32 s22, 0, 0x15c00
	s_movk_i32 s24, 0xffe0
	v_mov_b32_e32 v12, s23
	v_lshl_add_u32 v80, v4, 2, s10
	v_cmp_gt_u32_e64 s[14:15], s14, v4
	s_movk_i32 s21, 0x110
	v_add3_u32 v88, 0, v3, v86
	v_or_b32_e32 v3, s20, v156
	s_movk_i32 s20, 0x90
	v_add3_u32 v90, s22, v10, v86
	v_lshl_or_b32 v10, s19, 5, v72
	v_bfi_b32 v4, s24, v12, v4
	v_mul_lo_u32 v11, v10, s21
	v_mul_lo_u32 v4, v4, s20
	v_mul_u32_u24_e32 v9, 0x90, v9
	s_add_i32 s26, 0, 0x1e400
	v_add_u32_e32 v11, 0, v11
	s_and_b32 s25, s23, 0xffffffe0
	v_add3_u32 v92, 0, v4, v86
	v_or_b32_e32 v4, s16, v72
	v_add3_u32 v95, s17, v9, v86
	v_mul_lo_u32 v9, v10, s20
	v_mul_u32_u24_e32 v12, 0x90, v4
	v_add3_u32 v96, s26, v9, v86
	s_lshl_b32 s20, s18, 2
	v_lshlrev_b32_e32 v9, 4, v10
	v_lshl_add_u32 v10, s18, 6, v11
	s_lshl_b32 s18, s25, 1
	v_lshlrev_b32_e32 v154, 3, v5
	v_add3_u32 v93, s17, v12, v86
	v_or3_b32 v12, v168, s16, 32
	v_mul_u32_u24_e32 v4, 0x110, v4
	s_add_i32 s18, s18, s22
	v_add3_u32 v98, s18, v4, v154
	v_mul_u32_u24_e32 v4, 0x110, v12
	v_add3_u32 v99, s18, v4, v154
	s_movk_i32 s18, 0x880
	v_mul_lo_u32 v4, v7, s21
	v_mul_lo_u32 v7, v32, s18
	v_or_b32_e32 v7, v7, v33
	v_lshl_add_u32 v100, v7, 1, 0
	v_or_b32_e32 v7, 2, v3
	v_cmp_gt_u32_e64 s[22:23], v7, v2
	v_or_b32_e32 v7, 3, v3
	v_mul_u32_u24_e32 v5, 0x90, v2
	v_cmp_gt_u32_e64 s[24:25], v7, v2
	v_lshlrev_b32_e32 v7, 1, v3
	v_add3_u32 v101, s26, v5, v7
	v_or_b32_e32 v5, 8, v3
	v_cmp_gt_u32_e64 s[26:27], v5, v2
	v_or_b32_e32 v5, 9, v3
	v_cmp_gt_u32_e64 s[28:29], v5, v2
	v_or_b32_e32 v5, 10, v3
	v_cmp_gt_u32_e64 s[30:31], v5, v2
	v_or_b32_e32 v5, 11, v3
	v_cmp_gt_u32_e64 s[34:35], v5, v2
	v_or_b32_e32 v5, 16, v3
	v_cmp_gt_u32_e64 s[36:37], v5, v2
	v_or_b32_e32 v5, 17, v3
	s_lshl_b32 s19, s19, 9
	v_cmp_gt_u32_e64 s[38:39], v5, v2
	v_or_b32_e32 v5, 18, v3
	s_add_i32 s19, s19, 0
	v_cmp_gt_u32_e64 s[40:41], v5, v2
	v_or_b32_e32 v5, 19, v3
	s_add_i32 s19, s19, s20
	v_cmp_gt_u32_e64 s[42:43], v5, v2
	v_or_b32_e32 v5, 24, v3
	s_add_i32 s19, s19, 0x21200
	v_cmp_gt_u32_e64 s[44:45], v5, v2
	v_or_b32_e32 v5, 25, v3
	v_lshl_add_u32 v97, v168, 4, s19
	v_cmp_gt_u32_e64 s[18:19], v3, v2
	v_cmp_lt_u32_e64 s[20:21], v3, v2
	v_cmp_gt_u32_e64 s[46:47], v5, v2
	v_or_b32_e32 v5, 26, v3
	v_or_b32_e32 v3, 27, v3
	v_cmp_gt_u32_e64 s[48:49], v5, v2
	v_cmp_gt_u32_e64 s[50:51], v3, v2
	v_mbcnt_lo_u32_b32 v2, -1, 0
	v_lshl_add_u64 v[68:69], s[8:9], 0, v[66:67]
	v_add_u32_e32 v8, 0, v8
	v_mul_u32_u24_e32 v13, 0x90, v12
	v_lshlrev_b32_e32 v66, 2, v6
	v_mbcnt_hi_u32_b32 v103, -1, v2
	v_add_u32_e32 v2, 0, v9
	s_waitcnt vmcnt(1)
	v_mov_b64_e32 v[60:61], v[56:57]
	s_waitcnt vmcnt(0)
; DI unsigned pk2(float lo, float hi) { return f2bf(lo) | (f2bf(hi) << 16); }
; DI void hgrn2_block(const Args& a, unsigned char* lds, int bh, int tid, int wave, int lane) {
;     ...
;     f32x16 S0, S1;
; #pragma unroll
;     for (int e = 0; e < 16; ++e) { S0[e] = 0.f; S1[e] = 0.f; }
;     const int vt = wave & 3, tc = wave >> 2;
;     const float* gn = a.in[10];
;     __syncthreads();
;     unsigned short pq[16], pg[16], pv[16]; u32x4 phg[2];
;     { const bf16_t* base = Y1 + (size_t)(tok0 + 16 * tq) * NY1 + h * 128 + k;
; #pragma unroll
;       for (int j = 0; j < 16; ++j) { pq[j] = base[(size_t)j * NY1 + 2048]; pg[j] = base[(size_t)j * NY1 + 3072]; pv[j] = base[(size_t)j * NY1 + 4096]; }
;       const u32x4* hgp = (const u32x4*)(Y1 + (size_t)(tok0 + (tid >> 3)) * NY1 + 5120 + h * 128 + (tid & 7) * 16); phg[0] = hgp[0]; phg[1] = hgp[1]; }
;     for (int c = 0; c < 32; ++c) {
;         float fq_[16], ff[16]; unsigned vw[8]; u32x4 hgc[2] = {phg[0], phg[1]};
;     ...
;         { const int t = 32 * tc + r; const f32x4 q4 = *(const f32x4*)(rss + t * 4);
;           const float rs = rsqrtf((q4[0] + q4[1] + q4[2] + q4[3]) * (1.f / 128.f) + EPS);
;           bf16_t* Ost = Qt;
; #pragma unroll
;           for (int g = 0; g < 4; ++g) { u32x2 w; w.x = pk2(oacc[4 * g] * rs, oacc[4 * g + 1] * rs); w.y = pk2(oacc[4 * g + 2] * rs, oacc[4 * g + 3] * rs); *(u32x2*)(Ost + t * 136 + 32 * vt + 8 * g + 4 * hh) = w; }
	v_mov_b64_e32 v[64:65], v[52:53]
	v_cmp_lt_i32_e64 s[8:9], 0, v32
	v_cmp_lt_i32_e64 s[10:11], 1, v32
	v_cmp_lt_i32_e64 s[12:13], 2, v32
	v_add_u32_e32 v91, v11, v86
	v_add3_u32 v94, s17, v13, v86
	v_cmp_gt_u32_e64 s[16:17], 32, v168
	v_lshl_add_u64 v[70:71], s[68:69], 0, v[66:67]
	global_load_dwordx4 v[214:217], v[70:71], off
	global_load_dwordx4 v[218:221], v[70:71], off offset:16
	global_load_dwordx4 v[222:225], v[70:71], off offset:32
	global_load_dwordx4 v[226:229], v[70:71], off offset:48
	v_add_u32_e32 v102, 64, v34
	s_mov_b32 s82, 0xc2a00000
	s_movk_i32 s83, 0x7fff
	s_mov_b32 s86, 0xffff0000
	v_add_u32_e32 v104, 0x21200, v2
	v_mov_b32_e32 v105, 0x358637bd
	v_add_u32_e32 v106, v10, v154
	s_lshl_b32 s92, s87, 1
	v_lshlrev_b32_e32 v66, 1, v6
	v_add_u32_e32 v107, v8, v4
	v_mov_b32_e32 v108, 0x42a00000
	v_mov_b32_e32 v109, 1
	s_mov_b32 s87, s93
	v_mov_b32_e32 v2, v67
	v_mov_b32_e32 v3, v67
	v_mov_b32_e32 v4, v67
	v_mov_b32_e32 v5, v67
	v_mov_b32_e32 v6, v67
	v_mov_b32_e32 v7, v67
	v_mov_b32_e32 v8, v67
	v_mov_b32_e32 v9, v67
	v_mov_b32_e32 v10, v67
	v_mov_b32_e32 v11, v67
	v_mov_b32_e32 v12, v67
	v_mov_b32_e32 v13, v67
	v_mov_b32_e32 v14, v67
	v_mov_b32_e32 v15, v67
	v_mov_b32_e32 v16, v67
	v_mov_b32_e32 v17, v67
	v_mov_b32_e32 v18, v67
	v_mov_b32_e32 v19, v67
	v_mov_b32_e32 v20, v67
	v_mov_b32_e32 v21, v67
	v_mov_b32_e32 v22, v67
	v_mov_b32_e32 v23, v67
	v_mov_b32_e32 v24, v67
	v_mov_b32_e32 v25, v67
	v_mov_b32_e32 v26, v67
	v_mov_b32_e32 v27, v67
	v_mov_b32_e32 v28, v67
	v_mov_b32_e32 v29, v67
	v_mov_b32_e32 v30, v67
	v_mov_b32_e32 v31, v67
	v_mov_b32_e32 v32, v67
	v_mov_b32_e32 v33, v67
	v_mov_b32_e32 v144, v163
	v_mov_b32_e32 v142, v161
	v_mov_b32_e32 v140, v150
	v_mov_b32_e32 v138, v49
	v_mov_b32_e32 v136, v152
	v_mov_b32_e32 v134, v151
	v_mov_b32_e32 v133, v46
	v_mov_b32_e32 v130, v45
	v_mov_b32_e32 v128, v48
	v_mov_b32_e32 v125, v47
	v_mov_b32_e32 v122, v37
	v_mov_b32_e32 v119, v36
	v_mov_b32_e32 v116, v39
	v_mov_b32_e32 v113, v38
	v_mov_b32_e32 v146, v159
	v_mov_b32_e32 v149, v164
	v_mov_b32_e32 v112, v43
	v_mov_b32_e32 v115, v44
	v_mov_b32_e32 v120, v40
	v_mov_b32_e32 v121, v41
	v_mov_b32_e32 v124, v157
	v_mov_b32_e32 v129, v158
	v_mov_b32_e32 v131, v153
	v_mov_b32_e32 v132, v155
	v_mov_b32_e32 v135, v165
	v_mov_b32_e32 v137, v166
	v_mov_b32_e32 v139, v160
	v_mov_b32_e32 v141, v162
	v_mov_b32_e32 v143, v170
	v_mov_b32_e32 v145, v171
	v_mov_b32_e32 v147, v167
	v_mov_b32_e32 v148, v169
	v_mov_b64_e32 v[58:59], v[54:55]
	v_mov_b64_e32 v[62:63], v[50:51]
	s_branch .LBB0_227
.LBB0_226:
	s_or_b64 exec, exec, s[68:69]
	s_waitcnt lgkmcnt(0)
	s_barrier
	ds_read_b128 v[150:153], v104
	s_mov_b32 s68, 0x800000
	s_waitcnt vmcnt(8)
	v_mov_b32_e32 v163, v144
	v_mov_b32_e32 v161, v142
	s_waitcnt vmcnt(5)
	v_mov_b32_e32 v159, v146
	s_waitcnt lgkmcnt(0)
	v_add_f32_e32 v150, v150, v151
	v_add_f32_e32 v150, v152, v150
	v_add_f32_e32 v150, v153, v150
	v_fmamk_f32 v150, v150, 0x3c000000, v105
	v_cmp_gt_f32_e32 vcc, s68, v150
	v_mul_f32_e32 v151, 0x4b800000, v150
	v_mov_b32_e32 v152, v34
	v_cndmask_b32_e32 v150, v150, v151, vcc
	v_rsq_f32_e32 v150, v150
	v_mov_b32_e32 v153, v36
	v_mov_b32_e32 v36, v35
	s_mov_b64 s[68:69], 0x24dcc800
	v_mul_f32_e32 v151, 0x45800000, v150
	v_cndmask_b32_e32 v150, v150, v151, vcc
	v_pk_mul_f32 v[152:153], v[152:153], v[150:151] op_sel_hi:[1,0]
	v_pk_mul_f32 v[34:35], v[36:37], v[150:151] op_sel_hi:[1,0]
	v_and_b32_sdwa v37, v152, v109 dst_sel:DWORD dst_unused:UNUSED_PAD src0_sel:WORD_1 src1_sel:DWORD
	v_add3_u32 v37, v152, v37, s83
	v_and_b32_sdwa v151, v35, v109 dst_sel:DWORD dst_unused:UNUSED_PAD src0_sel:WORD_1 src1_sel:DWORD
	v_and_b32_sdwa v152, v34, v109 dst_sel:DWORD dst_unused:UNUSED_PAD src0_sel:WORD_1 src1_sel:DWORD
	v_and_b32_sdwa v36, v153, v109 dst_sel:DWORD dst_unused:UNUSED_PAD src0_sel:WORD_1 src1_sel:DWORD
	v_add3_u32 v35, v35, v151, s83
	v_add3_u32 v34, v34, v152, s83
	v_add3_u32 v36, v153, v36, s83
	v_and_b32_e32 v35, 0xffff0000, v35
	v_and_b32_e32 v34, 0xffff0000, v34
	v_or_b32_sdwa v35, v35, v36 dst_sel:DWORD dst_unused:UNUSED_PAD src0_sel:DWORD src1_sel:WORD_1
	v_or_b32_sdwa v34, v34, v37 dst_sel:DWORD dst_unused:UNUSED_PAD src0_sel:DWORD src1_sel:WORD_1
	v_mov_b32_e32 v36, v38
	v_mov_b32_e32 v37, v40
	v_pk_mul_f32 v[36:37], v[36:37], v[150:151] op_sel_hi:[1,0]
	v_mov_b32_e32 v40, v39
	v_pk_mul_f32 v[38:39], v[40:41], v[150:151] op_sel_hi:[1,0]
	v_and_b32_sdwa v40, v37, v109 dst_sel:DWORD dst_unused:UNUSED_PAD src0_sel:WORD_1 src1_sel:DWORD
	v_and_b32_sdwa v41, v36, v109 dst_sel:DWORD dst_unused:UNUSED_PAD src0_sel:WORD_1 src1_sel:DWORD
	v_add3_u32 v36, v36, v41, s83
	v_add3_u32 v37, v37, v40, s83
	v_and_b32_sdwa v40, v39, v109 dst_sel:DWORD dst_unused:UNUSED_PAD src0_sel:WORD_1 src1_sel:DWORD
	v_and_b32_sdwa v41, v38, v109 dst_sel:DWORD dst_unused:UNUSED_PAD src0_sel:WORD_1 src1_sel:DWORD
	v_add3_u32 v39, v39, v40, s83
	v_add3_u32 v38, v38, v41, s83
	v_and_b32_e32 v39, 0xffff0000, v39
	v_and_b32_e32 v38, 0xffff0000, v38
	v_or_b32_sdwa v37, v39, v37 dst_sel:DWORD dst_unused:UNUSED_PAD src0_sel:DWORD src1_sel:WORD_1
	v_or_b32_sdwa v36, v38, v36 dst_sel:DWORD dst_unused:UNUSED_PAD src0_sel:DWORD src1_sel:WORD_1
	ds_write2_b64 v106, v[34:35], v[36:37] offset1:2
	v_mov_b32_e32 v34, v42
	v_mov_b32_e32 v35, v44
	v_pk_mul_f32 v[34:35], v[34:35], v[150:151] op_sel_hi:[1,0]
	v_mov_b32_e32 v44, v43
	v_pk_mul_f32 v[36:37], v[44:45], v[150:151] op_sel_hi:[1,0]
	v_and_b32_sdwa v38, v35, v109 dst_sel:DWORD dst_unused:UNUSED_PAD src0_sel:WORD_1 src1_sel:DWORD
	v_and_b32_sdwa v39, v34, v109 dst_sel:DWORD dst_unused:UNUSED_PAD src0_sel:WORD_1 src1_sel:DWORD
	v_add3_u32 v34, v34, v39, s83
	v_add3_u32 v35, v35, v38, s83
; DI unsigned pk2(float lo, float hi) { return f2bf(lo) | (f2bf(hi) << 16); }
; DI void hgrn2_block(const Args& a, unsigned char* lds, int bh, int tid, int wave, int lane) {
;     ...
;           for (int g = 0; g < 4; ++g) { u32x2 w; w.x = pk2(oacc[4 * g] * rs, oacc[4 * g + 1] * rs); w.y = pk2(oacc[4 * g + 2] * rs, oacc[4 * g + 3] * rs); *(u32x2*)(Ost + t * 136 + 32 * vt + 8 * g + 4 * hh) = w; }
; #pragma unroll
;           for (int g = 0; g < 4; ++g) { u32x2 w0, w1; w0.x = pk2(S0[4 * g], S0[4 * g + 1]); w0.y = pk2(S0[4 * g + 2], S0[4 * g + 3]); w1.x = pk2(S1[4 * g], S1[4 * g + 1]); w1.y = pk2(S1[4 * g + 2], S1[4 * g + 3]);
;               *(u32x2*)(ST + (32 * vt2 + r) * 136 + 32 * ct + 8 * g + 4 * hh) = w0; *(u32x2*)(ST + (32 * (vt2 + 1) + r) * 136 + 32 * ct + 8 * g + 4 * hh) = w1; } }
;         __syncthreads();
	v_and_b32_sdwa v38, v37, v109 dst_sel:DWORD dst_unused:UNUSED_PAD src0_sel:WORD_1 src1_sel:DWORD
	v_and_b32_sdwa v39, v36, v109 dst_sel:DWORD dst_unused:UNUSED_PAD src0_sel:WORD_1 src1_sel:DWORD
	v_add3_u32 v37, v37, v38, s83
	v_add3_u32 v36, v36, v39, s83
	v_and_b32_e32 v37, 0xffff0000, v37
	v_and_b32_e32 v36, 0xffff0000, v36
	v_or_b32_sdwa v35, v37, v35 dst_sel:DWORD dst_unused:UNUSED_PAD src0_sel:DWORD src1_sel:WORD_1
	v_or_b32_sdwa v34, v36, v34 dst_sel:DWORD dst_unused:UNUSED_PAD src0_sel:DWORD src1_sel:WORD_1
	v_mov_b32_e32 v36, v46
	v_mov_b32_e32 v37, v48
	v_pk_mul_f32 v[36:37], v[36:37], v[150:151] op_sel_hi:[1,0]
	v_mov_b32_e32 v48, v47
	v_pk_mul_f32 v[38:39], v[48:49], v[150:151] op_sel_hi:[1,0]
	v_and_b32_sdwa v40, v37, v109 dst_sel:DWORD dst_unused:UNUSED_PAD src0_sel:WORD_1 src1_sel:DWORD
	v_and_b32_sdwa v41, v36, v109 dst_sel:DWORD dst_unused:UNUSED_PAD src0_sel:WORD_1 src1_sel:DWORD
	v_add3_u32 v36, v36, v41, s83
	v_add3_u32 v37, v37, v40, s83
	v_and_b32_sdwa v40, v39, v109 dst_sel:DWORD dst_unused:UNUSED_PAD src0_sel:WORD_1 src1_sel:DWORD
	v_and_b32_sdwa v41, v38, v109 dst_sel:DWORD dst_unused:UNUSED_PAD src0_sel:WORD_1 src1_sel:DWORD
	v_add3_u32 v39, v39, v40, s83
	v_add3_u32 v38, v38, v41, s83
	v_and_b32_e32 v39, 0xffff0000, v39
	v_and_b32_e32 v38, 0xffff0000, v38
	v_or_b32_sdwa v37, v39, v37 dst_sel:DWORD dst_unused:UNUSED_PAD src0_sel:DWORD src1_sel:WORD_1
	v_or_b32_sdwa v36, v38, v36 dst_sel:DWORD dst_unused:UNUSED_PAD src0_sel:DWORD src1_sel:WORD_1
	ds_write2_b64 v106, v[34:35], v[36:37] offset0:4 offset1:6
	v_bfe_u32 v34, v2, 16, 1
	v_add3_u32 v34, v2, v34, s83
	v_bfe_u32 v35, v3, 16, 1
	v_lshrrev_b32_e32 v34, 16, v34
	v_add3_u32 v35, v3, v35, s83
	v_and_or_b32 v34, v35, s86, v34
	v_bfe_u32 v35, v4, 16, 1
	v_add3_u32 v35, v4, v35, s83
	v_bfe_u32 v36, v5, 16, 1
	v_lshrrev_b32_e32 v35, 16, v35
	v_add3_u32 v36, v5, v36, s83
	v_and_or_b32 v35, v36, s86, v35
	v_bfe_u32 v36, v18, 16, 1
	v_add3_u32 v36, v18, v36, s83
	v_bfe_u32 v37, v19, 16, 1
	v_lshrrev_b32_e32 v36, 16, v36
	v_add3_u32 v37, v19, v37, s83
	v_and_or_b32 v36, v37, s86, v36
	v_bfe_u32 v37, v20, 16, 1
	v_add3_u32 v37, v20, v37, s83
	v_bfe_u32 v38, v21, 16, 1
	v_lshrrev_b32_e32 v37, 16, v37
	v_add3_u32 v38, v21, v38, s83
	v_and_or_b32 v37, v38, s86, v37
	ds_write_b64 v98, v[34:35]
	ds_write_b64 v99, v[36:37]
	v_bfe_u32 v34, v6, 16, 1
	v_add3_u32 v34, v6, v34, s83
	v_bfe_u32 v35, v7, 16, 1
	v_lshrrev_b32_e32 v34, 16, v34
	v_add3_u32 v35, v7, v35, s83
	v_and_or_b32 v34, v35, s86, v34
	v_bfe_u32 v35, v8, 16, 1
	v_add3_u32 v35, v8, v35, s83
	v_bfe_u32 v36, v9, 16, 1
	v_lshrrev_b32_e32 v35, 16, v35
	v_add3_u32 v36, v9, v36, s83
	v_and_or_b32 v35, v36, s86, v35
	v_bfe_u32 v36, v22, 16, 1
	v_add3_u32 v36, v22, v36, s83
	v_bfe_u32 v37, v23, 16, 1
	v_lshrrev_b32_e32 v36, 16, v36
	v_add3_u32 v37, v23, v37, s83
	v_and_or_b32 v36, v37, s86, v36
	v_bfe_u32 v37, v24, 16, 1
	v_add3_u32 v37, v24, v37, s83
	v_bfe_u32 v38, v25, 16, 1
	v_lshrrev_b32_e32 v37, 16, v37
	v_add3_u32 v38, v25, v38, s83
	v_and_or_b32 v37, v38, s86, v37
	ds_write_b64 v98, v[34:35] offset:16
	ds_write_b64 v99, v[36:37] offset:16
	v_bfe_u32 v34, v10, 16, 1
	v_add3_u32 v34, v10, v34, s83
	v_bfe_u32 v35, v11, 16, 1
	v_lshrrev_b32_e32 v34, 16, v34
	v_add3_u32 v35, v11, v35, s83
	v_and_or_b32 v34, v35, s86, v34
	v_bfe_u32 v35, v12, 16, 1
	v_add3_u32 v35, v12, v35, s83
	v_bfe_u32 v36, v13, 16, 1
	v_lshrrev_b32_e32 v35, 16, v35
	v_add3_u32 v36, v13, v36, s83
	v_and_or_b32 v35, v36, s86, v35
	v_bfe_u32 v36, v26, 16, 1
	v_add3_u32 v36, v26, v36, s83
	v_bfe_u32 v37, v27, 16, 1
	v_lshrrev_b32_e32 v36, 16, v36
	v_add3_u32 v37, v27, v37, s83
	v_and_or_b32 v36, v37, s86, v36
	v_bfe_u32 v37, v28, 16, 1
	v_add3_u32 v37, v28, v37, s83
	v_bfe_u32 v38, v29, 16, 1
	v_lshrrev_b32_e32 v37, 16, v37
	v_add3_u32 v38, v29, v38, s83
	v_and_or_b32 v37, v38, s86, v37
	ds_write_b64 v98, v[34:35] offset:32
	ds_write_b64 v99, v[36:37] offset:32
	v_bfe_u32 v34, v14, 16, 1
	v_add3_u32 v34, v14, v34, s83
	v_bfe_u32 v35, v15, 16, 1
	v_lshrrev_b32_e32 v34, 16, v34
	v_add3_u32 v35, v15, v35, s83
	v_and_or_b32 v34, v35, s86, v34
	v_bfe_u32 v35, v16, 16, 1
	v_add3_u32 v35, v16, v35, s83
	v_bfe_u32 v36, v17, 16, 1
	v_lshrrev_b32_e32 v35, 16, v35
	v_add3_u32 v36, v17, v36, s83
	v_and_or_b32 v35, v36, s86, v35
	v_bfe_u32 v36, v30, 16, 1
	v_add3_u32 v36, v30, v36, s83
	v_bfe_u32 v37, v31, 16, 1
	v_lshrrev_b32_e32 v36, 16, v36
	v_add3_u32 v37, v31, v37, s83
	v_and_or_b32 v36, v37, s86, v36
	v_bfe_u32 v37, v32, 16, 1
	v_add3_u32 v37, v32, v37, s83
	v_bfe_u32 v38, v33, 16, 1
	v_lshrrev_b32_e32 v37, 16, v37
	v_add3_u32 v38, v33, v38, s83
	v_and_or_b32 v37, v38, s86, v37
	ds_write_b64 v98, v[34:35] offset:48
	ds_write_b64 v99, v[36:37] offset:48
	s_waitcnt lgkmcnt(0)
	s_barrier
; __device__ __forceinline__ unsigned cvt_pk_bf16(float lo, float hi) { unsigned r; asm volatile("v_cvt_pk_bf16_f32 %0, %1, %2" : "=v"(r) : "v"(lo), "v"(hi)); return r; }
; DI float lo_f(unsigned w) { return __uint_as_float(w << 16); }
; DI float hi_f(unsigned w) { return __uint_as_float(w & 0xffff0000u); }
; DI void hgrn2_block(const Args& a, unsigned char* lds, int bh, int tid, int wave, int lane) {
;     ...
;         { const int t = tid >> 3, v0 = (tid & 7) * 16; const size_t grow = (size_t)(tok0 + 64 * c + t);
;           const u32x4* os = (const u32x4*)(Qt + t * 136 + v0);
;           u32x4* dst = (u32x4*)(AB + grow * D_ + 1024 + h * 128 + v0);
; #pragma unroll
;           for (int q = 0; q < 2; ++q) { const u32x4 ow = os[q], gw4 = hgc[q]; const float* gp = gn + v0 + 8 * q;
;               u32x4 w;
;               w.x = pg8::cvt_pk_bf16(lo_f(ow.x) * gp[0] * lo_f(gw4.x), hi_f(ow.x) * gp[1] * hi_f(gw4.x));
;               w.y = pg8::cvt_pk_bf16(lo_f(ow.y) * gp[2] * lo_f(gw4.y), hi_f(ow.y) * gp[3] * hi_f(gw4.y));
;               w.z = pg8::cvt_pk_bf16(lo_f(ow.z) * gp[4] * lo_f(gw4.z), hi_f(ow.z) * gp[5] * hi_f(gw4.z));
;               w.w = pg8::cvt_pk_bf16(lo_f(ow.w) * gp[6] * lo_f(gw4.w), hi_f(ow.w) * gp[7] * hi_f(gw4.w));
;               dst[q] = w; } }
	ds_read_b128 v[36:39], v107
	v_add_u32_e32 v34, s87, v78
	v_ashrrev_i32_e32 v35, 31, v34
	v_lshlrev_b64 v[34:35], 12, v[34:35]
	v_lshl_add_u64 v[34:35], s[84:85], 0, v[34:35]
	s_waitcnt lgkmcnt(0)
	v_lshlrev_b32_e32 v44, 16, v36
	v_and_b32_e32 v36, 0xffff0000, v36
	v_lshl_add_u64 v[34:35], v[34:35], 0, s[92:93]
	v_lshl_add_u64 v[40:41], v[34:35], 0, v[66:67]
	v_lshl_add_u64 v[34:35], v[40:41], 0, s[68:69]
	s_mov_b32 s68, 0x24dcc000
	v_add_co_u32_e32 v40, vcc, s68, v40
	s_add_i32 s87, s87, 64
	s_nop 0
	v_addc_co_u32_e32 v41, vcc, 0, v41, vcc
	s_cmpk_lg_i32 s87, 0x800
	v_mov_b32_e32 v150, v140
	v_mov_b32_e32 v49, v138
	v_mov_b32_e32 v152, v136
	v_mov_b32_e32 v151, v134
	v_mov_b32_e32 v46, v133
	v_mov_b32_e32 v45, v130
	v_mov_b32_e32 v48, v128
	v_mov_b32_e32 v47, v125
	s_waitcnt vmcnt(2)
	v_mov_b32_e32 v164, v149
	v_mov_b32_e32 v157, v124
	v_mov_b32_e32 v158, v129
	v_mov_b32_e32 v153, v131
	v_mov_b32_e32 v155, v132
	v_mov_b32_e32 v165, v135
	v_mov_b32_e32 v166, v137
	v_mov_b32_e32 v160, v139
	v_mov_b32_e32 v162, v141
	v_mov_b32_e32 v170, v143
	v_mov_b32_e32 v171, v145
	v_mov_b32_e32 v167, v147
	v_mov_b32_e32 v169, v148
	s_waitcnt vmcnt(0)
	v_mul_f32_e32 v42, v214, v44
	v_lshlrev_b32_e32 v44, 16, v54
	v_mul_f32_e32 v36, v215, v36
	v_and_b32_e32 v43, 0xffff0000, v54
	v_mul_f32_e32 v42, v42, v44
	v_mul_f32_e32 v36, v36, v43
	v_cvt_pk_bf16_f32 v36, v42, v36
	v_lshlrev_b32_e32 v44, 16, v37
	v_and_b32_e32 v37, 0xffff0000, v37
	v_mul_f32_e32 v42, v216, v44
	v_lshlrev_b32_e32 v44, 16, v55
	v_mul_f32_e32 v37, v217, v37
	v_and_b32_e32 v43, 0xffff0000, v55
	v_mul_f32_e32 v42, v42, v44
	v_mul_f32_e32 v37, v37, v43
	v_cvt_pk_bf16_f32 v37, v42, v37
	v_lshlrev_b32_e32 v44, 16, v38
	v_and_b32_e32 v38, 0xffff0000, v38
	v_mul_f32_e32 v42, v218, v44
	v_lshlrev_b32_e32 v44, 16, v56
	v_mul_f32_e32 v38, v219, v38
	v_and_b32_e32 v43, 0xffff0000, v56
	v_mul_f32_e32 v42, v42, v44
	v_mul_f32_e32 v38, v38, v43
	v_cvt_pk_bf16_f32 v38, v42, v38
	v_lshlrev_b32_e32 v44, 16, v39
	v_and_b32_e32 v39, 0xffff0000, v39
	v_mul_f32_e32 v39, v221, v39
	v_and_b32_e32 v43, 0xffff0000, v57
	v_mul_f32_e32 v42, v220, v44
	v_lshlrev_b32_e32 v44, 16, v57
	v_mul_f32_e32 v39, v39, v43
	v_mul_f32_e32 v42, v42, v44
	v_cvt_pk_bf16_f32 v39, v42, v39
	global_store_dwordx4 v[40:41], v[36:39], off offset:2048
	s_nop 1
	ds_read_b128 v[36:39], v107 offset:16
	v_mov_b64_e32 v[54:55], v[58:59]
	v_mov_b32_e32 v43, v112
	v_mov_b32_e32 v44, v115
	v_mov_b64_e32 v[56:57], v[60:61]
	s_waitcnt lgkmcnt(0)
	v_lshlrev_b32_e32 v42, 16, v36
	v_and_b32_e32 v36, 0xffff0000, v36
	v_mul_f32_e32 v40, v222, v42
	v_lshlrev_b32_e32 v42, 16, v50
	v_mul_f32_e32 v36, v223, v36
	v_and_b32_e32 v41, 0xffff0000, v50
	v_mul_f32_e32 v40, v40, v42
	v_mul_f32_e32 v36, v36, v41
	v_cvt_pk_bf16_f32 v36, v40, v36
	v_lshlrev_b32_e32 v42, 16, v37
	v_and_b32_e32 v37, 0xffff0000, v37
	v_mul_f32_e32 v40, v224, v42
	v_lshlrev_b32_e32 v42, 16, v51
	v_mul_f32_e32 v37, v225, v37
	v_and_b32_e32 v41, 0xffff0000, v51
	v_mul_f32_e32 v40, v40, v42
	v_mul_f32_e32 v37, v37, v41
	v_cvt_pk_bf16_f32 v37, v40, v37
	v_lshlrev_b32_e32 v42, 16, v38
	v_and_b32_e32 v38, 0xffff0000, v38
	v_mul_f32_e32 v40, v226, v42
	v_lshlrev_b32_e32 v42, 16, v52
	v_mul_f32_e32 v38, v227, v38
	v_and_b32_e32 v41, 0xffff0000, v52
	v_mul_f32_e32 v40, v40, v42
	v_mul_f32_e32 v38, v38, v41
	v_cvt_pk_bf16_f32 v38, v40, v38
	v_lshlrev_b32_e32 v42, 16, v39
	v_and_b32_e32 v39, 0xffff0000, v39
	v_mul_f32_e32 v39, v229, v39
	v_and_b32_e32 v41, 0xffff0000, v53
	v_mul_f32_e32 v40, v228, v42
	v_lshlrev_b32_e32 v42, 16, v53
	v_mul_f32_e32 v39, v39, v41
	v_mul_f32_e32 v40, v40, v42
	v_cvt_pk_bf16_f32 v39, v40, v39
	v_mov_b64_e32 v[50:51], v[62:63]
	global_store_dwordx4 v[34:35], v[36:39], off offset:16
	v_mov_b32_e32 v40, v120
	v_mov_b32_e32 v41, v121
	v_mov_b32_e32 v37, v122
	v_mov_b32_e32 v36, v119
	v_mov_b32_e32 v39, v116
	v_mov_b32_e32 v38, v113
	v_mov_b64_e32 v[52:53], v[64:65]
	s_cbranch_scc0 .LBB0_235
